# kernel entry: the second (dependent) kernarg s_load_dwordx16 merged into the first scalar-load round trip (spare SGPRs s[52:67], copied later)
# speedup vs baseline: 1.0018x; 1.0018x over previous
; #define LAS __attribute__((address_space(3)))
; __global__ void __launch_bounds__(NWAVES * 64, 2) fwd_megakernel(Args a) {
;     extern __shared__ __attribute__((aligned(16))) unsigned char lds_raw[];
;     LAS unsigned char* lds = (LAS unsigned char*)lds_raw;
;     const int tid = threadIdx.x, lane = tid & 63, wave = __builtin_amdgcn_readfirstlane(tid >> 6);
;     const int G = gridDim.x, gw = blockIdx.x * NWAVES + wave, NGW = G * NWAVES;
;     unsigned char* ws = a.ws;
;     float* SSC = (float*)(ws + WS_SSC); float* SSA = (float*)(ws + WS_SSA); float* SSF = (float*)(ws + WS_SSF);
;     bf16* WOUT = (bf16*)(ws + WS_WOUT); bf16* WIN = (bf16*)(ws + WS_WIN); bf16* XN = (bf16*)(ws + WS_XN); bf16* MIX = (bf16*)(ws + WS_MIX);
;     bf16* QKVG = (bf16*)(ws + WS_QKVG); float* HALO = (float*)(ws + WS_HALO); float* DEF = (float*)(ws + WS_DEF);
;     if (a.use_cg) cg::this_grid().sync();
_Z14fwd_megakernel4Args:
	s_load_dwordx2 s[96:97], s[0:1], 0x50
	s_load_dwordx4 s[4:7], s[0:1], 0x40
	s_load_dword s3, s[0:1], 0x58
	s_load_dword s99, s[0:1], 0x60
	s_load_dwordx16 s[52:67], s[0:1], 0x0
	s_add_u32 s48, s0, 0x60
	v_and_b32_e32 v230, 0x3ff, v0
	s_waitcnt lgkmcnt(0)
	v_writelane_b32 v253, s4, 0
	s_addc_u32 s49, s1, 0
	s_mov_b32 s98, s2
	v_writelane_b32 v253, s5, 1
	v_writelane_b32 v253, s6, 2
	s_movk_i32 s2, 0x3ff
	s_cmp_eq_u32 s3, 0
	v_readfirstlane_b32 s47, v230
	v_writelane_b32 v253, s7, 3
	s_cbranch_scc1 .LBB0_12
	v_lshrrev_b32_e32 v1, 20, v0
	v_lshrrev_b32_e32 v0, 10, v0
	v_or_b32_e32 v0, v0, v1
	v_and_or_b32 v0, v0, s2, v230
	v_cmp_eq_u32_e32 vcc, 0, v0
	s_barrier
	s_and_saveexec_b64 s[2:3], vcc
	s_cbranch_execz .LBB0_11
	buffer_wbl2 sc1
	s_load_dwordx2 s[4:5], s[48:49], 0x58
	s_mov_b64 s[6:7], exec
	v_mbcnt_lo_u32_b32 v0, s6, 0
	v_mbcnt_hi_u32_b32 v0, s7, v0
	v_cmp_eq_u32_e32 vcc, 0, v0
	s_waitcnt lgkmcnt(0)
	s_load_dword s10, s[4:5], 0x28
	s_and_saveexec_b64 s[8:9], vcc
	s_cbranch_execz .LBB0_4
	s_bcnt1_i32_b64 s6, s[6:7]
	v_mov_b32_e32 v1, 0
	v_mov_b32_e32 v2, s6
	global_atomic_add v1, v1, v2, s[4:5] offset:32 sc0

; #define LAS __attribute__((address_space(3)))
; __device__ __forceinline__ unsigned xb_add(unsigned* p, unsigned v) { return __hip_atomic_fetch_add(p, v, __ATOMIC_RELAXED, __HIP_MEMORY_SCOPE_AGENT); }
; __device__ __forceinline__ unsigned xb_xcc_id() { return (unsigned)__builtin_amdgcn_s_getreg((3 << 11) | 20) & 0xFu; }
; __device__ __forceinline__ XcdBarrier xcd_barrier_post(unsigned* bar, volatile LAS unsigned* st) {
;     XcdBarrier b; b.bar = bar; b.x = xb_xcc_id(); b.st = st;
;     if (threadIdx.x == 0) (void)xb_add(&bar[XB_XCNT(b.x)], 1u);
;     return b;
; __global__ void __launch_bounds__(NWAVES * 64, 2) fwd_megakernel(Args a) {
;     ...
;     const int tid = threadIdx.x, lane = tid & 63, wave = __builtin_amdgcn_readfirstlane(tid >> 6);
;     const int G = gridDim.x, gw = blockIdx.x * NWAVES + wave, NGW = G * NWAVES;
;     unsigned char* ws = a.ws;
;     float* SSC = (float*)(ws + WS_SSC); float* SSA = (float*)(ws + WS_SSA); float* SSF = (float*)(ws + WS_SSF);
;     bf16* WOUT = (bf16*)(ws + WS_WOUT); bf16* WIN = (bf16*)(ws + WS_WIN); bf16* XN = (bf16*)(ws + WS_XN); bf16* MIX = (bf16*)(ws + WS_MIX);
;     bf16* QKVG = (bf16*)(ws + WS_QKVG); float* HALO = (float*)(ws + WS_HALO); float* DEF = (float*)(ws + WS_DEF);
;     if (a.use_cg) cg::this_grid().sync();
;     volatile LAS unsigned* MISC = (volatile LAS unsigned*)(lds + LDS_MISC);
;     if (tid < 32) MISC[tid] = 0u;
;     __syncthreads();
;     const XcdBarrier bar = xcd_barrier_post((unsigned*)(ws + WS_BAR), MISC + 8);
.LBB0_12:
	v_cmp_gt_u32_e32 vcc, 32, v230
	v_lshl_add_u32 v81, v230, 2, 0
	s_and_saveexec_b64 s[2:3], vcc
	v_add_u32_e32 v0, 0x20400, v81
	v_mov_b32_e32 v1, 0
	ds_write_b32 v0, v1
	s_or_b64 exec, exec, s[2:3]
	s_mov_b64 s[4:5], s[52:53]
	s_mov_b64 s[6:7], s[54:55]
	s_mov_b64 s[8:9], s[56:57]
	s_mov_b64 s[10:11], s[58:59]
	s_mov_b64 s[12:13], s[60:61]
	s_mov_b64 s[14:15], s[62:63]
	s_mov_b64 s[16:17], s[64:65]
	s_mov_b64 s[18:19], s[66:67]
	s_add_u32 s0, s96, 0x180000
	s_addc_u32 s1, s97, 0
	s_waitcnt lgkmcnt(0)
	s_barrier
	v_writelane_b32 v253, s4, 4
	v_cmp_eq_u32_e64 s[2:3], 0, v230
	s_nop 0
	v_writelane_b32 v253, s5, 5
	v_writelane_b32 v253, s6, 6
	v_writelane_b32 v253, s7, 7
	v_writelane_b32 v253, s8, 8
	v_writelane_b32 v253, s9, 9
	v_writelane_b32 v253, s10, 10
	v_writelane_b32 v253, s11, 11
	v_writelane_b32 v253, s12, 12
	v_writelane_b32 v253, s13, 13
	v_writelane_b32 v253, s14, 14
	v_writelane_b32 v253, s15, 15
	v_writelane_b32 v253, s16, 16
	v_writelane_b32 v253, s17, 17
	v_writelane_b32 v253, s18, 18
	v_writelane_b32 v253, s19, 19
	v_writelane_b32 v253, s0, 20
	s_nop 1
	v_writelane_b32 v253, s1, 21
	s_getreg_b32 s0, hwreg(HW_REG_XCC_ID, 0, 4)
	s_and_b32 s0, s0, 15
	v_writelane_b32 v253, s0, 22
	s_mov_b64 s[0:1], exec
	v_writelane_b32 v253, s2, 23
	s_nop 1
	v_writelane_b32 v253, s3, 24
	s_and_b64 s[2:3], s[0:1], s[2:3]
	s_mov_b64 exec, s[2:3]
	s_cbranch_execz .LBB0_17
	s_mov_b64 s[2:3], exec
	v_mbcnt_lo_u32_b32 v0, s2, 0
	v_mbcnt_hi_u32_b32 v0, s3, v0
	v_cmp_eq_u32_e32 vcc, 0, v0
	s_and_b64 s[4:5], exec, vcc
	s_mov_b64 exec, s[4:5]
	s_cbranch_execz .LBB0_17
	v_readlane_b32 s4, v253, 22
	s_bcnt1_i32_b64 s2, s[2:3]
	s_lshl_b32 s4, s4, 8
	v_mov_b32_e32 v1, s2
	v_readlane_b32 s2, v253, 20
	v_mov_b32_e32 v0, s4
	v_readlane_b32 s3, v253, 21
	s_nop 4
	global_atomic_add v0, v1, s[2:3] offset:1024
